# attention softmax half-wave max/sum exchange via v_permlane32_swap instead of ds_bpermute
# speedup vs baseline: 1.0001x; 1.0001x over previous
.LBB0_522:
	s_cmp_lt_u32 s15, s10
	s_cselect_b32 s4, 0, s10
	s_cselect_b32 s5, s40, s7
	s_lshl_b32 s4, s4, 5
	s_sub_i32 s4, s5, s4
	s_add_i32 s30, s21, s4
	s_add_i32 s4, s11, s15
	v_add_u32_e32 v66, s30, v189
	s_cmp_lt_u32 s4, s10
	v_ashrrev_i32_e32 v67, 31, v66
	s_cselect_b32 s4, 0, s10
	v_lshlrev_b64 v[66:67], 10, v[66:67]
	s_cselect_b32 s5, s40, s7
	s_lshl_b32 s4, s4, 5
	v_add_u32_e32 v228, 0xec00, v193
	v_add_u32_e32 v229, 0x4800, v192
	v_add_u32_e32 v230, 0x6c00, v192
	v_lshl_add_u64 v[66:67], v[178:179], 0, v[66:67]
	s_sub_i32 s4, s5, s4
	s_add_i32 s5, s33, s21
	s_waitcnt vmcnt(9)
	ds_write_b128 v191, v[130:133]
	s_waitcnt vmcnt(8)
	ds_write2_b64 v192, v[134:135], v[136:137] offset1:1
	s_waitcnt vmcnt(7)
	ds_write_b128 v191, v[142:145] offset:12800
	s_waitcnt vmcnt(6)
	ds_write2_b64 v228, v[138:139], v[140:141] offset1:1
	s_waitcnt vmcnt(5)
	ds_write_b128 v191, v[150:153] offset:25600
	s_waitcnt vmcnt(4)
	ds_write2_b64 v229, v[146:147], v[148:149] offset1:1
	s_waitcnt vmcnt(3)
	ds_write_b128 v191, v[158:161] offset:38400
	s_waitcnt vmcnt(2)
	ds_write2_b64 v230, v[154:155], v[156:157] offset1:1
	s_waitcnt vmcnt(1)
	ds_write_b128 v194, v[162:165] offset:256
	s_waitcnt vmcnt(0)
	ds_write_b128 v195, v[166:169] offset:256
	s_waitcnt lgkmcnt(0)
	s_barrier
	global_load_dwordx4 v[130:133], v[66:67], off
	v_lshl_add_u64 v[66:67], s[30:31], 1, v[180:181]
	s_add_i32 s30, s5, s4
	s_add_i32 s4, s4, s21
	global_load_dwordx4 v[134:137], v[66:67], off
	v_add_u32_e32 v66, s4, v201
	s_add_i32 s4, s18, s15
	s_cmp_lt_u32 s4, s10
	v_ashrrev_i32_e32 v67, 31, v66
	s_cselect_b32 s4, 0, s10
	v_lshlrev_b64 v[66:67], 10, v[66:67]
	s_cselect_b32 s5, s40, s7
	s_lshl_b32 s4, s4, 5
	v_lshl_add_u64 v[66:67], v[178:179], 0, v[66:67]
	s_sub_i32 s4, s5, s4
	s_add_i32 s5, s39, s21
	global_load_dwordx4 v[142:145], v[66:67], off
	v_lshl_add_u64 v[66:67], s[30:31], 1, v[180:181]
	s_add_i32 s30, s5, s4
	s_add_i32 s4, s4, s21
	global_load_dwordx4 v[138:141], v[66:67], off
	v_add_u32_e32 v66, s4, v199
	s_add_i32 s4, s19, s15
	s_cmp_lt_u32 s4, s10
	v_ashrrev_i32_e32 v67, 31, v66
	s_cselect_b32 s4, 0, s10
	v_lshlrev_b64 v[66:67], 10, v[66:67]
	s_cselect_b32 s5, s40, s7
	s_lshl_b32 s4, s4, 5
	v_lshl_add_u64 v[66:67], v[178:179], 0, v[66:67]
	s_sub_i32 s4, s5, s4
	s_add_i32 s5, s20, s21
	global_load_dwordx4 v[150:153], v[66:67], off
	v_lshl_add_u64 v[66:67], s[30:31], 1, v[180:181]
	s_add_i32 s30, s5, s4
	s_add_i32 s4, s4, s21
	global_load_dwordx4 v[146:149], v[66:67], off
	v_add_u32_e32 v66, s4, v200
	v_ashrrev_i32_e32 v67, 31, v66
	v_lshlrev_b64 v[66:67], 10, v[66:67]
	v_lshl_add_u64 v[66:67], v[178:179], 0, v[66:67]
	global_load_dwordx4 v[158:161], v[66:67], off
	v_lshl_add_u64 v[66:67], s[30:31], 1, v[180:181]
	v_cmp_gt_i32_e32 vcc, s10, v197
	v_mov_b32_e32 v68, s10
	global_load_dwordx4 v[154:157], v[66:67], off
	v_cndmask_b32_e64 v66, v68, 0, vcc
	v_mov_b32_e32 v69, s7
	v_mov_b32_e32 v70, s40
	v_cndmask_b32_e32 v67, v69, v70, vcc
	v_lshlrev_b32_e32 v66, 5, v66
	v_sub_u32_e32 v66, v67, v66
	v_add3_u32 v66, v198, s21, v66
	v_ashrrev_i32_e32 v67, 31, v66
	v_lshlrev_b64 v[66:67], 7, v[66:67]
	v_lshl_add_u64 v[66:67], v[182:183], 0, v[66:67]
	global_load_dwordx4 v[162:165], v[66:67], off
	v_add_u32_e32 v66, s18, v197
	v_cmp_gt_i32_e32 vcc, s10, v66
	v_mov_b32_e32 v0, v185
	v_mov_b32_e32 v235, v184
	v_cndmask_b32_e64 v66, v68, 0, vcc
	v_cndmask_b32_e32 v67, v69, v70, vcc
	v_lshlrev_b32_e32 v66, 5, v66
	v_sub_u32_e32 v66, v67, v66
	v_add3_u32 v66, v196, s21, v66
	v_ashrrev_i32_e32 v67, 31, v66
	v_lshlrev_b64 v[66:67], 7, v[66:67]
	v_lshl_add_u64 v[66:67], v[182:183], 0, v[66:67]
	global_load_dwordx4 v[166:169], v[66:67], off
	ds_read_b128 v[66:69], v190
	ds_read_b128 v[236:239], v190 offset:32
	s_waitcnt lgkmcnt(1)
	v_mfma_f32_32x32x16_bf16 v[66:81], v[66:69], v[118:121], 0
	v_add_u32_e32 v234, 0xc800, v227
	v_add_u32_e32 v231, 0xd800, v227
	s_add_i32 s21, s21, 32
	s_add_i32 s15, s15, 1
	v_add_u32_e32 v197, 1, v197
	s_cmp_lg_u32 s33, s21
	s_waitcnt lgkmcnt(0)
	v_mfma_f32_32x32x16_bf16 v[66:81], v[236:239], v[110:113], v[66:81]
	ds_read_b128 v[236:239], v190 offset:64
	s_waitcnt lgkmcnt(0)
	v_mfma_f32_32x32x16_bf16 v[66:81], v[236:239], v[106:109], v[66:81]
	ds_read_b128 v[236:239], v190 offset:96
	s_waitcnt lgkmcnt(0)
	v_mfma_f32_32x32x16_bf16 v[66:81], v[236:239], v[102:105], v[66:81]
	ds_read_b128 v[236:239], v190 offset:128
	s_waitcnt lgkmcnt(0)
	v_mfma_f32_32x32x16_bf16 v[66:81], v[236:239], v[98:101], v[66:81]
	ds_read_b128 v[236:239], v190 offset:160
	s_waitcnt lgkmcnt(0)
	v_mfma_f32_32x32x16_bf16 v[66:81], v[236:239], v[94:97], v[66:81]
	ds_read_b128 v[236:239], v190 offset:192
	s_waitcnt lgkmcnt(0)
	v_mfma_f32_32x32x16_bf16 v[66:81], v[236:239], v[90:93], v[66:81]
	ds_read_b128 v[236:239], v190 offset:224
	s_waitcnt lgkmcnt(0)
	v_mfma_f32_32x32x16_bf16 v[66:81], v[236:239], v[86:89], v[66:81]
	ds_read_b128 v[236:239], v190 offset:256
	s_waitcnt lgkmcnt(0)
	v_mfma_f32_32x32x16_bf16 v[66:81], v[236:239], v[122:125], v[66:81]
	ds_read_b128 v[236:239], v190 offset:288
	s_waitcnt lgkmcnt(0)
	v_mfma_f32_32x32x16_bf16 v[66:81], v[236:239], v[114:117], v[66:81]
	ds_read_b128 v[236:239], v190 offset:320
	s_waitcnt lgkmcnt(0)
	v_mfma_f32_32x32x16_bf16 v[66:81], v[236:239], v[126:129], v[66:81]
	ds_read_b128 v[236:239], v190 offset:352
	s_waitcnt lgkmcnt(0)
	v_mfma_f32_32x32x16_bf16 v[66:81], v[236:239], v[82:85], v[66:81]
	s_nop 11
	v_max_f32_e32 v184, v67, v67
	v_max_f32_e32 v185, v66, v66
	v_max_f32_e32 v184, v185, v184
	v_max3_f32 v184, v184, v68, v69
	v_max3_f32 v184, v184, v70, v71
	v_max3_f32 v184, v184, v72, v73
	v_max3_f32 v184, v184, v74, v75
	v_max3_f32 v184, v184, v76, v77
	v_max3_f32 v184, v184, v78, v79
	v_max3_f32 v184, v184, v80, v81
	v_mov_b32_e32 v185, v184
	s_nop 1
	v_permlane32_swap_b32 v185, v184
	s_waitcnt lgkmcnt(0)
	v_max3_f32 v185, v0, v184, v185
	v_mov_b32_e32 v184, v81
	v_pk_mul_f32 v[232:233], v[184:185], s[26:27] op_sel_hi:[1,0]
	v_sub_f32_e32 v0, v0, v185
	v_fma_f32 v66, v66, s26, -v233
	v_exp_f32_e32 v66, v66
	v_fma_f32 v67, v67, s26, -v233
	v_exp_f32_e32 v67, v67
	v_fma_f32 v68, v68, s26, -v233
	v_exp_f32_e32 v68, v68
	v_fma_f32 v69, v69, s26, -v233
	v_exp_f32_e32 v69, v69
	v_fma_f32 v70, v70, s26, -v233
	v_exp_f32_e32 v70, v70
	v_fma_f32 v71, v71, s26, -v233
	v_add_f32_e32 v184, 0, v66
	v_exp_f32_e32 v71, v71
	v_fma_f32 v72, v72, s26, -v233
	v_add_f32_e32 v184, v67, v184
	v_exp_f32_e32 v72, v72
	v_fma_f32 v73, v73, s26, -v233
	v_add_f32_e32 v184, v68, v184
	v_exp_f32_e32 v73, v73
	v_fma_f32 v74, v74, s26, -v233
	v_add_f32_e32 v184, v69, v184
	v_exp_f32_e32 v74, v74
	v_fma_f32 v75, v75, s26, -v233
	v_add_f32_e32 v184, v70, v184
	v_exp_f32_e32 v75, v75
	v_fma_f32 v76, v76, s26, -v233
	v_add_f32_e32 v184, v71, v184
	v_exp_f32_e32 v76, v76
	v_fma_f32 v77, v77, s26, -v233
	v_add_f32_e32 v184, v72, v184
	v_exp_f32_e32 v77, v77
	v_fma_f32 v78, v78, s26, -v233
	v_add_f32_e32 v184, v73, v184
	v_exp_f32_e32 v78, v78
	v_fma_f32 v79, v79, s26, -v233
	v_add_f32_e32 v184, v74, v184
	v_exp_f32_e32 v79, v79
	v_fma_f32 v80, v80, s26, -v233
	v_add_f32_e32 v184, v75, v184
	v_exp_f32_e32 v80, v80
	v_sub_f32_e32 v81, v232, v233
	v_add_f32_e32 v184, v76, v184
	v_exp_f32_e32 v81, v81
	v_add_f32_e32 v184, v77, v184
	v_add_f32_e32 v184, v78, v184
	v_mul_f32_e32 v0, 0x3dd53b94, v0
	v_add_f32_e32 v184, v79, v184
	v_exp_f32_e32 v0, v0
	v_add_f32_e32 v184, v80, v184
	v_add_f32_e32 v184, v81, v184
	v_cvt_pk_bf16_f32 v66, v66, v67
	v_cvt_pk_bf16_f32 v67, v68, v69
	v_cvt_pk_bf16_f32 v68, v70, v71
	v_cvt_pk_bf16_f32 v69, v72, v73
	v_cvt_pk_bf16_f32 v70, v74, v75
	v_cvt_pk_bf16_f32 v71, v76, v77
	v_cvt_pk_bf16_f32 v72, v78, v79
	v_cvt_pk_bf16_f32 v73, v80, v81
	ds_read2_b64 v[74:77], v234 offset1:2
	ds_read2_b64 v[78:81], v234 offset0:4 offset1:6
	v_pk_mul_f32 v[16:17], v[16:17], v[0:1] op_sel_hi:[1,0]
	v_pk_mul_f32 v[14:15], v[14:15], v[0:1] op_sel_hi:[1,0]
	v_pk_mul_f32 v[12:13], v[12:13], v[0:1] op_sel_hi:[1,0]
	v_pk_mul_f32 v[10:11], v[10:11], v[0:1] op_sel_hi:[1,0]
	v_pk_mul_f32 v[8:9], v[8:9], v[0:1] op_sel_hi:[1,0]
	v_pk_mul_f32 v[6:7], v[6:7], v[0:1] op_sel_hi:[1,0]
	v_pk_mul_f32 v[4:5], v[4:5], v[0:1] op_sel_hi:[1,0]
	v_pk_mul_f32 v[2:3], v[2:3], v[0:1] op_sel_hi:[1,0]
	v_add_u32_e32 v233, 0xd000, v227
	v_pk_mul_f32 v[48:49], v[48:49], v[0:1] op_sel_hi:[1,0]
	s_waitcnt lgkmcnt(1)
	v_mfma_f32_32x32x16_bf16 v[2:17], v[74:77], v[66:69], v[2:17]
	ds_read2_b64 v[74:77], v233 offset0:32 offset1:34
	v_mul_f32_e64 v46, v46, v0
	v_mul_f32_e64 v47, v47, v0
	v_mul_f32_e64 v44, v44, v0
	v_mul_f32_e64 v45, v45, v0
	v_pk_mul_f32 v[42:43], v[42:43], v[0:1] op_sel_hi:[1,0]
	v_pk_mul_f32 v[40:41], v[40:41], v[0:1] op_sel_hi:[1,0]
	v_pk_mul_f32 v[38:39], v[38:39], v[0:1] op_sel_hi:[1,0]
	v_pk_mul_f32 v[36:37], v[36:37], v[0:1] op_sel_hi:[1,0]
	v_pk_mul_f32 v[34:35], v[34:35], v[0:1] op_sel_hi:[1,0]
	v_pk_mul_f32 v[64:65], v[64:65], v[0:1] op_sel_hi:[1,0]
	v_pk_mul_f32 v[62:63], v[62:63], v[0:1] op_sel_hi:[1,0]
	s_waitcnt lgkmcnt(0)
	v_mfma_f32_32x32x16_bf16 v[34:49], v[74:77], v[66:69], v[34:49]
	ds_read2_b64 v[74:77], v233 offset0:36 offset1:38
	v_mul_f32_e64 v60, v60, v0
	v_mul_f32_e64 v61, v61, v0
	v_mul_f32_e64 v58, v58, v0
	v_mul_f32_e64 v59, v59, v0
	v_pk_mul_f32 v[56:57], v[56:57], v[0:1] op_sel_hi:[1,0]
	v_pk_mul_f32 v[54:55], v[54:55], v[0:1] op_sel_hi:[1,0]
	v_pk_mul_f32 v[52:53], v[52:53], v[0:1] op_sel_hi:[1,0]
	v_pk_mul_f32 v[50:51], v[50:51], v[0:1] op_sel_hi:[1,0]
	s_waitcnt lgkmcnt(0)
	v_mfma_f32_32x32x16_bf16 v[34:49], v[74:77], v[70:73], v[34:49]
	ds_read2_b64 v[74:77], v231 offset0:64 offset1:66
	v_add_u32_e32 v232, 0xe000, v227
	v_mul_f32_e64 v32, v32, v0
	v_mul_f32_e64 v33, v33, v0
	v_mul_f32_e64 v30, v30, v0
	v_mul_f32_e64 v31, v31, v0
	v_pk_mul_f32 v[28:29], v[28:29], v[0:1] op_sel_hi:[1,0]
	v_pk_mul_f32 v[26:27], v[26:27], v[0:1] op_sel_hi:[1,0]
	v_pk_mul_f32 v[24:25], v[24:25], v[0:1] op_sel_hi:[1,0]
	s_waitcnt lgkmcnt(0)
	v_mfma_f32_32x32x16_bf16 v[50:65], v[74:77], v[66:69], v[50:65]
	ds_read2_b64 v[74:77], v231 offset0:68 offset1:70
	v_mul_f32_e64 v22, v22, v0
	v_mul_f32_e64 v23, v23, v0
	v_mul_f32_e64 v20, v20, v0
	v_mul_f32_e64 v21, v21, v0
	v_pk_mul_f32 v[18:19], v[18:19], v[0:1] op_sel_hi:[1,0]
	v_fmac_f32_e32 v184, v235, v0
	s_waitcnt lgkmcnt(0)
	v_mfma_f32_32x32x16_bf16 v[50:65], v[74:77], v[70:73], v[50:65]
	ds_read2_b64 v[74:77], v232 offset0:96 offset1:98
	s_waitcnt lgkmcnt(0)
	v_mfma_f32_32x32x16_bf16 v[18:33], v[74:77], v[66:69], v[18:33]
	ds_read2_b64 v[66:69], v232 offset0:100 offset1:102
	s_waitcnt lgkmcnt(0)
	s_barrier
	v_mfma_f32_32x32x16_bf16 v[2:17], v[78:81], v[70:73], v[2:17]
	v_mfma_f32_32x32x16_bf16 v[18:33], v[66:69], v[70:73], v[18:33]
	s_cbranch_scc1 .LBB0_522
	s_waitcnt vmcnt(9)
	ds_write_b128 v191, v[130:133]
	s_waitcnt vmcnt(8)
	ds_write2_b64 v192, v[134:135], v[136:137] offset1:1
	s_waitcnt vmcnt(7)
	ds_write_b128 v191, v[142:145] offset:12800
	s_waitcnt vmcnt(6)
	ds_write2_b64 v228, v[138:139], v[140:141] offset1:1
	s_waitcnt vmcnt(5)
	ds_write_b128 v191, v[150:153] offset:25600
	s_waitcnt vmcnt(4)
	ds_write2_b64 v229, v[146:147], v[148:149] offset1:1
	s_waitcnt vmcnt(3)
	ds_write_b128 v191, v[158:161] offset:38400
	s_waitcnt vmcnt(2)
	ds_write2_b64 v230, v[154:155], v[156:157] offset1:1
	s_waitcnt vmcnt(1)
	ds_write_b128 v194, v[162:165] offset:256
	s_waitcnt vmcnt(0)
	ds_write_b128 v195, v[166:169] offset:256
	s_waitcnt lgkmcnt(0)
	s_barrier
	ds_read_b128 v[66:69], v190
	ds_read_b128 v[130:133], v190 offset:32
	s_waitcnt lgkmcnt(1)
	v_mfma_f32_32x32x16_bf16 v[66:81], v[66:69], v[118:121], 0
	v_readlane_b32 s4, v253, 17
	s_mov_b32 s7, 0xf149f2ca
	s_mov_b32 s39, s31
	s_waitcnt lgkmcnt(0)
	v_mfma_f32_32x32x16_bf16 v[66:81], v[130:133], v[110:113], v[66:81]
	ds_read_b128 v[110:113], v190 offset:64
	ds_read_b128 v[118:121], v190 offset:96
	s_waitcnt lgkmcnt(1)
	v_mfma_f32_32x32x16_bf16 v[66:81], v[110:113], v[106:109], v[66:81]
	v_ashrrev_i32_e32 v110, 6, v188
	s_waitcnt lgkmcnt(0)
	v_mfma_f32_32x32x16_bf16 v[66:81], v[118:121], v[102:105], v[66:81]
	ds_read_b128 v[102:105], v190 offset:128
	ds_read_b128 v[106:109], v190 offset:160
	s_waitcnt lgkmcnt(1)
	v_mfma_f32_32x32x16_bf16 v[66:81], v[102:105], v[98:101], v[66:81]
	s_waitcnt lgkmcnt(0)
	v_mfma_f32_32x32x16_bf16 v[66:81], v[106:109], v[94:97], v[66:81]
	ds_read_b128 v[94:97], v190 offset:192
	ds_read_b128 v[98:101], v190 offset:224
	s_waitcnt lgkmcnt(1)
	v_mfma_f32_32x32x16_bf16 v[66:81], v[94:97], v[90:93], v[66:81]
	s_waitcnt lgkmcnt(0)
	v_mfma_f32_32x32x16_bf16 v[66:81], v[98:101], v[86:89], v[66:81]
	ds_read_b128 v[86:89], v190 offset:256
	ds_read_b128 v[90:93], v190 offset:288
	s_waitcnt lgkmcnt(1)
	v_mfma_f32_32x32x16_bf16 v[66:81], v[86:89], v[122:125], v[66:81]
	s_waitcnt lgkmcnt(0)
	v_mfma_f32_32x32x16_bf16 v[66:81], v[90:93], v[114:117], v[66:81]
	ds_read_b128 v[90:93], v190 offset:320
	ds_read_b128 v[86:89], v190 offset:352
	s_waitcnt lgkmcnt(1)
	v_mfma_f32_32x32x16_bf16 v[66:81], v[90:93], v[126:129], v[66:81]
	ds_read2_b64 v[90:93], v234 offset1:2
	ds_read2_b64 v[94:97], v234 offset0:4 offset1:6
	ds_read2_b64 v[98:101], v233 offset0:32 offset1:34
	s_waitcnt lgkmcnt(3)
	v_mfma_f32_32x32x16_bf16 v[66:81], v[86:89], v[82:85], v[66:81]
	ds_read2_b64 v[84:87], v233 offset0:36 offset1:38
	ds_read2_b64 v[102:105], v231 offset0:64 offset1:66
	s_nop 9
	v_max_f32_e32 v0, v67, v67
	v_max_f32_e32 v82, v66, v66
	v_max_f32_e32 v0, v82, v0
	v_max3_f32 v0, v0, v68, v69
	v_max3_f32 v0, v0, v70, v71
	v_max3_f32 v0, v0, v72, v73
	v_max3_f32 v0, v0, v74, v75
	v_max3_f32 v0, v0, v76, v77
	v_max3_f32 v0, v0, v78, v79
	v_max3_f32 v0, v0, v80, v81
	v_mov_b32_e32 v83, v0
	v_mov_b32_e32 v88, v81
	v_and_b32_e32 v82, 1, v110
	v_permlane32_swap_b32 v83, v0
	s_waitcnt lgkmcnt(0)
	v_max3_f32 v89, v185, v0, v83
	v_sub_f32_e32 v0, v185, v89
	v_pk_mul_f32 v[106:107], v[88:89], s[26:27] op_sel_hi:[1,0]
	v_mul_f32_e32 v0, 0x3dd53b94, v0
	v_fma_f32 v66, v66, s26, -v107
	v_fma_f32 v67, v67, s26, -v107
	v_fma_f32 v68, v68, s26, -v107
	v_fma_f32 v69, v69, s26, -v107
	v_fma_f32 v70, v70, s26, -v107
	v_fma_f32 v71, v71, s26, -v107
	v_fma_f32 v72, v72, s26, -v107
	v_fma_f32 v73, v73, s26, -v107
	v_exp_f32_e32 v0, v0
	v_exp_f32_e32 v88, v66
	v_exp_f32_e32 v111, v67
	v_exp_f32_e32 v112, v68
	v_exp_f32_e32 v113, v69
	v_exp_f32_e32 v114, v70
	v_exp_f32_e32 v115, v71
	v_exp_f32_e32 v116, v72
	v_exp_f32_e32 v117, v73
	v_fma_f32 v74, v74, s26, -v107
	v_fma_f32 v75, v75, s26, -v107
	v_fma_f32 v76, v76, s26, -v107
	v_fma_f32 v77, v77, s26, -v107
	v_fma_f32 v78, v78, s26, -v107
	v_fma_f32 v79, v79, s26, -v107
	v_fma_f32 v80, v80, s26, -v107
	v_sub_f32_e32 v83, v106, v107
	v_exp_f32_e32 v118, v74
	v_exp_f32_e32 v119, v75
	v_exp_f32_e32 v120, v76
	v_exp_f32_e32 v121, v77
	v_exp_f32_e32 v122, v78
	v_exp_f32_e32 v123, v79
	v_exp_f32_e32 v124, v80
	v_pk_mul_f32 v[80:81], v[16:17], v[0:1] op_sel_hi:[1,0]
	v_pk_mul_f32 v[78:79], v[14:15], v[0:1] op_sel_hi:[1,0]
	v_pk_mul_f32 v[76:77], v[12:13], v[0:1] op_sel_hi:[1,0]
	v_pk_mul_f32 v[74:75], v[10:11], v[0:1] op_sel_hi:[1,0]
	v_pk_mul_f32 v[72:73], v[8:9], v[0:1] op_sel_hi:[1,0]
	v_pk_mul_f32 v[70:71], v[6:7], v[0:1] op_sel_hi:[1,0]
	v_pk_mul_f32 v[68:69], v[4:5], v[0:1] op_sel_hi:[1,0]
	v_pk_mul_f32 v[66:67], v[2:3], v[0:1] op_sel_hi:[1,0]
	v_pk_mul_f32 v[16:17], v[48:49], v[0:1] op_sel_hi:[1,0]
	v_cvt_pk_bf16_f32 v106, v88, v111
	v_cvt_pk_bf16_f32 v107, v112, v113
	v_cvt_pk_bf16_f32 v108, v114, v115
	v_cvt_pk_bf16_f32 v109, v116, v117
	v_pk_mul_f32 v[14:15], v[46:47], v[0:1] op_sel_hi:[1,0]
	v_pk_mul_f32 v[12:13], v[44:45], v[0:1] op_sel_hi:[1,0]
	v_pk_mul_f32 v[10:11], v[42:43], v[0:1] op_sel_hi:[1,0]
	v_pk_mul_f32 v[8:9], v[40:41], v[0:1] op_sel_hi:[1,0]
	v_pk_mul_f32 v[6:7], v[38:39], v[0:1] op_sel_hi:[1,0]
	v_pk_mul_f32 v[4:5], v[36:37], v[0:1] op_sel_hi:[1,0]
	v_pk_mul_f32 v[2:3], v[34:35], v[0:1] op_sel_hi:[1,0]
	v_pk_mul_f32 v[48:49], v[64:65], v[0:1] op_sel_hi:[1,0]
	v_pk_mul_f32 v[46:47], v[62:63], v[0:1] op_sel_hi:[1,0]
	v_pk_mul_f32 v[44:45], v[60:61], v[0:1] op_sel_hi:[1,0]
	v_pk_mul_f32 v[42:43], v[58:59], v[0:1] op_sel_hi:[1,0]
	v_pk_mul_f32 v[40:41], v[56:57], v[0:1] op_sel_hi:[1,0]
	v_pk_mul_f32 v[38:39], v[54:55], v[0:1] op_sel_hi:[1,0]
	v_pk_mul_f32 v[36:37], v[52:53], v[0:1] op_sel_hi:[1,0]
	v_pk_mul_f32 v[34:35], v[50:51], v[0:1] op_sel_hi:[1,0]
	ds_read2_b64 v[50:53], v231 offset0:68 offset1:70
	v_add_f32_e32 v54, 0, v88
	v_mfma_f32_32x32x16_bf16 v[34:49], v[102:105], v[106:109], v[34:49]
	v_add_f32_e32 v54, v111, v54
	v_exp_f32_e32 v83, v83
	v_add_f32_e32 v54, v112, v54
	v_add_f32_e32 v54, v113, v54
	v_add_f32_e32 v58, v114, v54
	ds_read2_b64 v[54:57], v232 offset0:96 offset1:98
	v_cvt_pk_bf16_f32 v62, v118, v119
	v_cvt_pk_bf16_f32 v63, v120, v121
	v_cvt_pk_bf16_f32 v64, v122, v123
	v_cvt_pk_bf16_f32 v65, v124, v83
	v_mfma_f32_32x32x16_bf16 v[66:81], v[90:93], v[106:109], v[66:81]
	v_mul_f32_e64 v32, v32, v0
	v_mul_f32_e64 v33, v33, v0
	v_mul_f32_e64 v30, v30, v0
	v_mul_f32_e64 v31, v31, v0
	v_mul_f32_e64 v28, v28, v0
	v_mul_f32_e64 v29, v29, v0
	v_pk_mul_f32 v[26:27], v[26:27], v[0:1] op_sel_hi:[1,0]
	v_pk_mul_f32 v[24:25], v[24:25], v[0:1] op_sel_hi:[1,0]
	v_pk_mul_f32 v[22:23], v[22:23], v[0:1] op_sel_hi:[1,0]
	v_pk_mul_f32 v[20:21], v[20:21], v[0:1] op_sel_hi:[1,0]
	s_waitcnt lgkmcnt(1)
	v_mfma_f32_32x32x16_bf16 v[34:49], v[50:53], v[62:65], v[34:49]
	v_add_f32_e32 v50, v115, v58
	v_add_f32_e32 v50, v116, v50
	v_add_f32_e32 v50, v117, v50
	v_add_f32_e32 v50, v118, v50
	v_add_f32_e32 v50, v119, v50
	v_pk_mul_f32 v[18:19], v[18:19], v[0:1] op_sel_hi:[1,0]
	v_add_f32_e32 v58, v120, v50
	ds_read2_b64 v[50:53], v232 offset0:100 offset1:102
	s_waitcnt lgkmcnt(1)
	v_mfma_f32_32x32x16_bf16 v[18:33], v[54:57], v[106:109], v[18:33]
	v_add_f32_e32 v54, v121, v58
	v_add_f32_e32 v54, v122, v54
	v_add_f32_e32 v54, v123, v54
	v_add_f32_e32 v54, v124, v54
	v_add_f32_e32 v54, v83, v54
	v_fmac_f32_e32 v54, v184, v0
	v_mov_b32_e32 v0, v54
	v_mfma_f32_32x32x16_bf16 v[2:17], v[98:101], v[106:109], v[2:17]
	s_nop 1
	v_permlane32_swap_b32 v0, v54
	s_waitcnt lgkmcnt(0)
	s_barrier
	v_add_f32_e32 v0, v54, v0
	v_mfma_f32_32x32x16_bf16 v[66:81], v[94:97], v[62:65], v[66:81]
	v_mfma_f32_32x32x16_bf16 v[18:33], v[50:53], v[62:65], v[18:33]
	v_lshlrev_b32_e32 v50, 9, v110
	v_lshlrev_b32_e32 v51, 2, v186
	v_add3_u32 v50, s4, v50, v51
	ds_write2st64_b32 v50, v89, v0 offset1:1
	v_lshlrev_b32_e32 v0, 14, v110
	v_add3_u32 v0, 0, v0, v51
	v_mfma_f32_32x32x16_bf16 v[2:17], v[84:87], v[62:65], v[2:17]
	s_nop 3
	ds_write2st64_b32 v0, v66, v67 offset1:1
	ds_write2st64_b32 v0, v68, v69 offset0:2 offset1:3
	ds_write2st64_b32 v0, v70, v71 offset0:4 offset1:5
	ds_write2st64_b32 v0, v72, v73 offset0:6 offset1:7
	ds_write2st64_b32 v0, v74, v75 offset0:8 offset1:9
	ds_write2st64_b32 v0, v76, v77 offset0:10 offset1:11
	ds_write2st64_b32 v0, v78, v79 offset0:12 offset1:13
	ds_write2st64_b32 v0, v80, v81 offset0:14 offset1:15
	ds_write2st64_b32 v0, v2, v3 offset0:16 offset1:17
	ds_write2st64_b32 v0, v4, v5 offset0:18 offset1:19
	ds_write2st64_b32 v0, v6, v7 offset0:20 offset1:21
	ds_write2st64_b32 v0, v8, v9 offset0:22 offset1:23
	ds_write2st64_b32 v0, v10, v11 offset0:24 offset1:25
	ds_write2st64_b32 v0, v12, v13 offset0:26 offset1:27
	ds_write2st64_b32 v0, v14, v15 offset0:28 offset1:29
	ds_write2st64_b32 v0, v16, v17 offset0:30 offset1:31
	ds_write2st64_b32 v0, v34, v35 offset0:32 offset1:33
	ds_write2st64_b32 v0, v36, v37 offset0:34 offset1:35
	ds_write2st64_b32 v0, v38, v39 offset0:36 offset1:37
	ds_write2st64_b32 v0, v40, v41 offset0:38 offset1:39
	ds_write2st64_b32 v0, v42, v43 offset0:40 offset1:41
	ds_write2st64_b32 v0, v44, v45 offset0:42 offset1:43
	ds_write2st64_b32 v0, v46, v47 offset0:44 offset1:45
	ds_write2st64_b32 v0, v48, v49 offset0:46 offset1:47
	ds_write2st64_b32 v0, v18, v19 offset0:48 offset1:49
	ds_write2st64_b32 v0, v20, v21 offset0:50 offset1:51
	ds_write2st64_b32 v0, v22, v23 offset0:52 offset1:53
	ds_write2st64_b32 v0, v24, v25 offset0:54 offset1:55
	ds_write2st64_b32 v0, v26, v27 offset0:56 offset1:57
	ds_write2st64_b32 v0, v28, v29 offset0:58 offset1:59
	ds_write2st64_b32 v0, v30, v31 offset0:60 offset1:61
	ds_write2st64_b32 v0, v32, v33 offset0:62 offset1:63
	v_lshlrev_b32_e32 v0, 9, v82
	v_add3_u32 v0, s4, v0, v51
	s_waitcnt lgkmcnt(0)
	s_barrier
	ds_read2st64_b32 v[4:5], v0 offset1:1
	ds_read2st64_b32 v[6:7], v0 offset0:4 offset1:5
	ds_read2st64_b32 v[8:9], v0 offset0:8 offset1:9
	ds_read2st64_b32 v[10:11], v0 offset0:12 offset1:13
	s_lshl_b64 s[4:5], s[38:39], 11
	s_waitcnt lgkmcnt(2)
	v_max3_f32 v0, v4, s7, v6
	s_add_u32 s7, s80, s4
	s_waitcnt lgkmcnt(0)
	v_max3_f32 v0, v0, v8, v10
	v_sub_f32_e32 v2, v4, v0
	v_mul_f32_e32 v2, 0x3dd53b94, v2
	v_exp_f32_e32 v3, v2
	v_sub_f32_e32 v2, v6, v0
	v_mul_f32_e32 v2, 0x3dd53b94, v2
	v_exp_f32_e32 v2, v2
	v_mov_b32_e32 v4, v7
	s_addc_u32 s10, s81, s5
	v_pk_mul_f32 v[6:7], v[4:5], v[2:3]
	v_sub_f32_e32 v4, v8, v0
	v_sub_f32_e32 v0, v10, v0
	v_mul_f32_e32 v4, 0x3dd53b94, v4
	v_mul_f32_e32 v0, 0x3dd53b94, v0
	v_exp_f32_e32 v5, v4
	v_exp_f32_e32 v4, v0
	v_add_f32_e32 v0, 0, v7
	v_mov_b32_e32 v8, v11
	v_add_f32_e32 v0, v6, v0
	v_pk_mul_f32 v[6:7], v[8:9], v[4:5]
	s_nop 0
	v_add_f32_e32 v0, v7, v0
	v_add_f32_e32 v0, v6, v0
	v_div_scale_f32 v6, s[4:5], v0, v0, 1.0
	v_rcp_f32_e32 v7, v6
	s_lshl_b32 s4, s14, 1
	s_add_u32 s38, s7, s4
	s_addc_u32 s39, s10, 0
	v_fma_f32 v8, -v6, v7, 1.0
	v_fmac_f32_e32 v7, v8, v7
	v_div_scale_f32 v8, vcc, 1.0, v0, 1.0
	v_mul_f32_e32 v9, v8, v7
	v_fma_f32 v10, -v6, v9, v8
	v_fmac_f32_e32 v9, v10, v7
	v_fma_f32 v6, -v6, v9, v8
	v_div_fmas_f32 v6, v6, v7, v9
	v_div_fixup_f32 v0, v6, v0, 1.0
	v_lshl_add_u32 v6, v82, 14, 0
	v_lshlrev_b32_e32 v7, 12, v177
	v_add3_u32 v7, v6, v7, v51
	ds_read2st64_b32 v[8:9], v7 offset1:1
	ds_read2st64_b32 v[10:11], v7 offset0:128 offset1:129
	v_mov_b32_e32 v6, v3
	v_add_u32_e32 v24, 0x10000, v7
	v_add_u32_e32 v25, 0x18000, v7
	v_add_u32_e32 v27, 0x10100, v7
	v_add_u32_e32 v28, 0x18100, v7
	ds_read2st64_b32 v[12:13], v7 offset0:2 offset1:3
	ds_read2st64_b32 v[14:15], v7 offset0:4 offset1:5
	ds_read2st64_b32 v[16:17], v7 offset0:6 offset1:7
	s_waitcnt lgkmcnt(4)
	v_pk_fma_f32 v[8:9], v[8:9], v[6:7], 0 op_sel_hi:[1,0,0]
	v_add_u32_e32 v31, 0x18300, v7
	ds_read2st64_b32 v[18:19], v7 offset0:130 offset1:131
	ds_read2st64_b32 v[20:21], v7 offset0:132 offset1:133
	ds_read2st64_b32 v[22:23], v7 offset0:134 offset1:135
	s_waitcnt lgkmcnt(6)
	v_pk_fma_f32 v[8:9], v[10:11], v[2:3], v[8:9] op_sel_hi:[1,0,1]
	v_mov_b32_e32 v10, v5
	v_add_u32_e32 v3, 0x10200, v7
	v_add_u32_e32 v5, 0x18200, v7
	v_add_u32_e32 v11, 0x10300, v7
	ds_read_b32 v24, v24
	ds_read_b32 v26, v25
	ds_read_b32 v25, v27
	ds_read_b32 v27, v28
	ds_read_b32 v28, v3
	ds_read_b32 v30, v5
	ds_read_b32 v29, v11
	ds_read_b32 v31, v31
	s_waitcnt lgkmcnt(13)
	v_pk_fma_f32 v[12:13], v[6:7], v[12:13], 0 op_sel_hi:[0,1,0]
	s_waitcnt lgkmcnt(5)
	v_pk_fma_f32 v[8:9], v[10:11], v[24:25], v[8:9] op_sel_hi:[0,1,1]
	v_pk_fma_f32 v[12:13], v[2:3], v[18:19], v[12:13] op_sel_hi:[0,1,1]
	v_add_u32_e32 v3, 0x10400, v7
	v_pk_fma_f32 v[14:15], v[6:7], v[14:15], 0 op_sel_hi:[0,1,0]
	s_waitcnt lgkmcnt(4)
	v_pk_fma_f32 v[8:9], v[4:5], v[26:27], v[8:9] op_sel_hi:[0,1,1]
	s_waitcnt lgkmcnt(1)
	v_pk_fma_f32 v[12:13], v[10:11], v[28:29], v[12:13] op_sel_hi:[0,1,1]
	v_add_u32_e32 v11, 0x10500, v7
	v_add_u32_e32 v24, 0x18500, v7
	v_pk_fma_f32 v[14:15], v[2:3], v[20:21], v[14:15] op_sel_hi:[0,1,1]
	v_add_u32_e32 v25, 0x10600, v7
	v_add_u32_e32 v26, 0x18600, v7
	v_add_u32_e32 v27, 0x10700, v7
	s_waitcnt lgkmcnt(0)
	v_pk_fma_f32 v[12:13], v[4:5], v[30:31], v[12:13] op_sel_hi:[0,1,1]
	v_add_u32_e32 v5, 0x18400, v7
	v_add_u32_e32 v28, 0x18700, v7
	ds_read_b32 v18, v3
	ds_read_b32 v20, v5
	ds_read_b32 v19, v11
	ds_read_b32 v21, v24
	ds_read_b32 v24, v25
	ds_read_b32 v26, v26
	ds_read_b32 v25, v27
	ds_read_b32 v27, v28
	s_waitcnt lgkmcnt(5)
	v_pk_fma_f32 v[14:15], v[10:11], v[18:19], v[14:15] op_sel_hi:[0,1,1]
	s_waitcnt lgkmcnt(4)
	v_pk_fma_f32 v[14:15], v[4:5], v[20:21], v[14:15] op_sel_hi:[0,1,1]
	ds_read2st64_b32 v[18:19], v7 offset0:8 offset1:9
	ds_read2st64_b32 v[20:21], v7 offset0:136 offset1:137
	v_pk_fma_f32 v[16:17], v[6:7], v[16:17], 0 op_sel_hi:[0,1,0]
	v_pk_fma_f32 v[16:17], v[2:3], v[22:23], v[16:17] op_sel_hi:[0,1,1]
	s_waitcnt lgkmcnt(3)
	v_pk_fma_f32 v[16:17], v[10:11], v[24:25], v[16:17] op_sel_hi:[0,1,1]
	s_waitcnt lgkmcnt(2)
	v_pk_fma_f32 v[16:17], v[4:5], v[26:27], v[16:17] op_sel_hi:[0,1,1]
	v_add_u32_e32 v3, 0x10800, v7
	v_add_u32_e32 v35, 0x18900, v7
	ds_read2st64_b32 v[22:23], v7 offset0:10 offset1:11
	ds_read2st64_b32 v[24:25], v7 offset0:12 offset1:13
	ds_read2st64_b32 v[26:27], v7 offset0:14 offset1:15
	s_waitcnt lgkmcnt(4)
	v_pk_fma_f32 v[18:19], v[6:7], v[18:19], 0 op_sel_hi:[0,1,0]
	v_add_u32_e32 v36, 0x10a00, v7
	v_add_u32_e32 v37, 0x18a00, v7
	v_add_u32_e32 v39, 0x10b00, v7
	v_add_u32_e32 v5, 0x18800, v7
	v_add_u32_e32 v11, 0x10900, v7
	ds_read2st64_b32 v[28:29], v7 offset0:138 offset1:139
	ds_read2st64_b32 v[30:31], v7 offset0:140 offset1:141
	ds_read2st64_b32 v[32:33], v7 offset0:142 offset1:143
	s_waitcnt lgkmcnt(6)
	v_pk_fma_f32 v[18:19], v[2:3], v[20:21], v[18:19] op_sel_hi:[0,1,1]
	v_add_u32_e32 v40, 0x18b00, v7
	ds_read_b32 v20, v3
	ds_read_b32 v34, v5
	ds_read_b32 v21, v11
	ds_read_b32 v35, v35
	ds_read_b32 v36, v36
	ds_read_b32 v38, v37
	ds_read_b32 v37, v39
	ds_read_b32 v39, v40
	s_waitcnt lgkmcnt(5)
	v_pk_fma_f32 v[18:19], v[10:11], v[20:21], v[18:19] op_sel_hi:[0,1,1]
	v_pk_fma_f32 v[20:21], v[6:7], v[22:23], 0 op_sel_hi:[0,1,0]
	v_pk_fma_f32 v[20:21], v[2:3], v[28:29], v[20:21] op_sel_hi:[0,1,1]
	v_add_u32_e32 v3, 0x10c00, v7
	v_pk_fma_f32 v[22:23], v[6:7], v[24:25], 0 op_sel_hi:[0,1,0]
	s_waitcnt lgkmcnt(4)
	v_pk_fma_f32 v[18:19], v[4:5], v[34:35], v[18:19] op_sel_hi:[0,1,1]
	s_waitcnt lgkmcnt(1)
	v_pk_fma_f32 v[20:21], v[10:11], v[36:37], v[20:21] op_sel_hi:[0,1,1]
	v_add_u32_e32 v29, 0x18d00, v7
	v_pk_fma_f32 v[22:23], v[2:3], v[30:31], v[22:23] op_sel_hi:[0,1,1]
	v_add_u32_e32 v30, 0x10e00, v7
	v_add_u32_e32 v31, 0x18e00, v7
	v_add_u32_e32 v35, 0x10f00, v7
	s_waitcnt lgkmcnt(0)
	v_pk_fma_f32 v[20:21], v[4:5], v[38:39], v[20:21] op_sel_hi:[0,1,1]
	v_add_u32_e32 v5, 0x18c00, v7
	v_add_u32_e32 v11, 0x10d00, v7
	v_add_u32_e32 v7, 0x18f00, v7
	ds_read_b32 v24, v3
	ds_read_b32 v28, v5
	ds_read_b32 v25, v11
	ds_read_b32 v29, v29
	ds_read_b32 v30, v30
	ds_read_b32 v34, v31
	ds_read_b32 v31, v35
	ds_read_b32 v35, v7
	v_pk_fma_f32 v[6:7], v[6:7], v[26:27], 0 op_sel_hi:[0,1,0]
	v_pk_fma_f32 v[2:3], v[2:3], v[32:33], v[6:7] op_sel_hi:[0,1,1]
	s_waitcnt lgkmcnt(5)
	v_pk_fma_f32 v[22:23], v[10:11], v[24:25], v[22:23] op_sel_hi:[0,1,1]
	s_waitcnt lgkmcnt(1)
	v_pk_fma_f32 v[2:3], v[10:11], v[30:31], v[2:3] op_sel_hi:[0,1,1]
	v_pk_fma_f32 v[22:23], v[4:5], v[28:29], v[22:23] op_sel_hi:[0,1,1]
	s_waitcnt lgkmcnt(0)
	v_pk_fma_f32 v[2:3], v[4:5], v[34:35], v[2:3] op_sel_hi:[0,1,1]
	v_pk_mul_f32 v[8:9], v[8:9], v[0:1] op_sel_hi:[1,0]
	v_pk_mul_f32 v[12:13], v[0:1], v[12:13] op_sel_hi:[0,1]
	v_pk_mul_f32 v[14:15], v[0:1], v[14:15] op_sel_hi:[0,1]
	v_pk_mul_f32 v[16:17], v[0:1], v[16:17] op_sel_hi:[0,1]
	v_pk_mul_f32 v[18:19], v[0:1], v[18:19] op_sel_hi:[0,1]
	v_pk_mul_f32 v[20:21], v[0:1], v[20:21] op_sel_hi:[0,1]
	v_pk_mul_f32 v[22:23], v[0:1], v[22:23] op_sel_hi:[0,1]
	v_pk_mul_f32 v[2:3], v[0:1], v[2:3] op_sel_hi:[0,1]
	v_lshlrev_b32_e32 v0, 11, v175
	v_lshl_or_b32 v0, v82, 16, v0
	v_lshlrev_b32_e32 v6, 5, v177
	v_lshl_add_u64 v[4:5], s[38:39], 0, v[0:1]
	v_ashrrev_i32_e32 v7, 31, v6
	v_lshl_add_u64 v[4:5], v[6:7], 1, v[4:5]
	v_mov_b32_e32 v177, v1
	v_lshl_add_u64 v[4:5], v[4:5], 0, v[176:177]
	s_mov_b64 s[4:5], 0x4328400
	v_lshl_add_u64 v[6:7], v[4:5], 0, s[4:5]
	s_mov_b32 s4, 0x4328000
	v_add_co_u32_e32 v4, vcc, s4, v4
	v_cvt_pk_bf16_f32 v8, v8, v9
	v_cvt_pk_bf16_f32 v9, v12, v13
	v_addc_co_u32_e32 v5, vcc, 0, v5, vcc
	global_store_dwordx2 v[4:5], v[8:9], off offset:1024
	v_cvt_pk_bf16_f32 v4, v14, v15
	v_cvt_pk_bf16_f32 v5, v16, v17
	global_store_dwordx2 v[6:7], v[4:5], off offset:16
	v_cvt_pk_bf16_f32 v4, v18, v19
	v_cvt_pk_bf16_f32 v5, v20, v21
	global_store_dwordx2 v[6:7], v[4:5], off offset:32
	v_cvt_pk_bf16_f32 v4, v22, v23
	v_cvt_pk_bf16_f32 v5, v2, v3
	global_store_dwordx2 v[6:7], v[4:5], off offset:48
	s_barrier
	s_mov_b64 s[14:15], 0

.LBB0_592:
	s_cmp_lt_u32 s14, s7
	s_cselect_b32 s4, 0, s7
	s_cselect_b32 s5, s24, s1
	s_lshl_b32 s4, s4, 5
	s_sub_i32 s4, s5, s4
	s_add_i32 s30, s15, s4
	s_add_i32 s4, s10, s14
	v_add_u32_e32 v66, s30, v158
	s_cmp_lt_u32 s4, s7
	v_ashrrev_i32_e32 v67, 31, v66
	s_cselect_b32 s4, 0, s7
	v_lshlrev_b64 v[66:67], 9, v[66:67]
	s_cselect_b32 s5, s24, s1
	s_lshl_b32 s4, s4, 5
	v_add_u32_e32 v166, 0x8800, v161
	v_add_u32_e32 v167, 0xac00, v161
	v_add_u32_e32 v168, 0xd000, v161
	v_add_u32_e32 v169, 0xf400, v161
	v_lshl_add_u64 v[66:67], v[150:151], 0, v[66:67]
	s_sub_i32 s4, s5, s4
	s_add_i32 s5, s20, s15
	s_waitcnt vmcnt(7)
	ds_write_b128 v160, v[118:121]
	s_waitcnt vmcnt(6)
	ds_write2_b64 v166, v[114:115], v[116:117] offset1:1
	s_waitcnt vmcnt(5)
	ds_write_b128 v160, v[126:129] offset:8704
	s_waitcnt vmcnt(4)
	ds_write2_b64 v167, v[122:123], v[124:125] offset1:1
	s_waitcnt vmcnt(3)
	ds_write_b128 v160, v[134:137] offset:17408
	s_waitcnt vmcnt(2)
	ds_write2_b64 v168, v[130:131], v[132:133] offset1:1
	s_waitcnt vmcnt(1)
	ds_write_b128 v160, v[142:145] offset:26112
	s_waitcnt vmcnt(0)
	ds_write2_b64 v169, v[138:139], v[140:141] offset1:1
	s_waitcnt lgkmcnt(0)
	s_barrier
	global_load_dwordx4 v[118:121], v[66:67], off
	v_lshl_add_u64 v[66:67], s[30:31], 1, v[152:153]
	s_add_i32 s30, s5, s4
	s_add_i32 s4, s4, s15
	global_load_dwordx4 v[114:117], v[66:67], off
	v_add_u32_e32 v66, s4, v164
	s_add_i32 s4, s11, s14
	s_cmp_lt_u32 s4, s7
	v_ashrrev_i32_e32 v67, 31, v66
	s_cselect_b32 s4, 0, s7
	v_lshlrev_b64 v[66:67], 9, v[66:67]
	s_cselect_b32 s5, s24, s1
	s_lshl_b32 s4, s4, 5
	v_lshl_add_u64 v[66:67], v[150:151], 0, v[66:67]
	s_sub_i32 s4, s5, s4
	s_add_i32 s5, s21, s15
	global_load_dwordx4 v[126:129], v[66:67], off
	v_lshl_add_u64 v[66:67], s[30:31], 1, v[152:153]
	s_add_i32 s30, s5, s4
	s_add_i32 s4, s4, s15
	global_load_dwordx4 v[122:125], v[66:67], off
	v_add_u32_e32 v66, s4, v162
	s_add_i32 s4, s18, s14
	s_cmp_lt_u32 s4, s7
	v_ashrrev_i32_e32 v67, 31, v66
	s_cselect_b32 s4, 0, s7
	v_lshlrev_b64 v[66:67], 9, v[66:67]
	s_cselect_b32 s5, s24, s1
	s_lshl_b32 s4, s4, 5
	v_lshl_add_u64 v[66:67], v[150:151], 0, v[66:67]
	s_sub_i32 s4, s5, s4
	s_add_i32 s5, s19, s15
	global_load_dwordx4 v[134:137], v[66:67], off
	v_lshl_add_u64 v[66:67], s[30:31], 1, v[152:153]
	s_add_i32 s30, s5, s4
	s_add_i32 s4, s4, s15
	global_load_dwordx4 v[130:133], v[66:67], off
	v_add_u32_e32 v66, s4, v163
	v_ashrrev_i32_e32 v67, 31, v66
	v_lshlrev_b64 v[66:67], 9, v[66:67]
	v_lshl_add_u64 v[66:67], v[150:151], 0, v[66:67]
	global_load_dwordx4 v[142:145], v[66:67], off
	v_lshl_add_u64 v[66:67], s[30:31], 1, v[152:153]
	global_load_dwordx4 v[138:141], v[66:67], off
	ds_read_b128 v[66:69], v159
	ds_read_b128 v[176:179], v159 offset:32
	s_waitcnt lgkmcnt(1)
	v_mfma_f32_32x32x16_bf16 v[66:81], v[66:69], v[110:113], 0
	v_mov_b32_e32 v0, v149
	v_mov_b32_e32 v175, v148
	s_add_i32 s15, s15, 32
	s_add_i32 s14, s14, 1
	s_cmp_lg_u32 s20, s15
	s_waitcnt lgkmcnt(0)
	v_mfma_f32_32x32x16_bf16 v[66:81], v[176:179], v[106:109], v[66:81]
	ds_read_b128 v[176:179], v159 offset:64
	s_waitcnt lgkmcnt(0)
	v_mfma_f32_32x32x16_bf16 v[66:81], v[176:179], v[102:105], v[66:81]
	ds_read_b128 v[176:179], v159 offset:96
	s_waitcnt lgkmcnt(0)
	v_mfma_f32_32x32x16_bf16 v[66:81], v[176:179], v[98:101], v[66:81]
	ds_read_b128 v[176:179], v159 offset:128
	s_waitcnt lgkmcnt(0)
	v_mfma_f32_32x32x16_bf16 v[66:81], v[176:179], v[94:97], v[66:81]
	ds_read_b128 v[176:179], v159 offset:160
	s_waitcnt lgkmcnt(0)
	v_mfma_f32_32x32x16_bf16 v[66:81], v[176:179], v[90:93], v[66:81]
	ds_read_b128 v[176:179], v159 offset:192
	s_waitcnt lgkmcnt(0)
	v_mfma_f32_32x32x16_bf16 v[66:81], v[176:179], v[86:89], v[66:81]
	ds_read_b128 v[176:179], v159 offset:224
	s_waitcnt lgkmcnt(0)
	v_mfma_f32_32x32x16_bf16 v[66:81], v[176:179], v[82:85], v[66:81]
	s_nop 11
	v_max_f32_e32 v148, v67, v67
	v_max_f32_e32 v149, v66, v66
	v_max_f32_e32 v148, v149, v148
	v_max3_f32 v148, v148, v68, v69
	v_max3_f32 v148, v148, v70, v71
	v_max3_f32 v148, v148, v72, v73
	v_max3_f32 v148, v148, v74, v75
	v_max3_f32 v148, v148, v76, v77
	v_max3_f32 v148, v148, v78, v79
	v_max3_f32 v148, v148, v80, v81
	v_mov_b32_e32 v149, v148
	s_nop 1
	v_permlane32_swap_b32 v149, v148
	s_waitcnt lgkmcnt(0)
	v_max3_f32 v149, v0, v148, v149
	v_mov_b32_e32 v148, v81
	v_pk_mul_f32 v[176:177], v[148:149], s[28:29] op_sel_hi:[1,0]
	v_sub_f32_e32 v0, v0, v149
	v_fma_f32 v70, v70, s28, -v177
	v_exp_f32_e32 v81, v70
	v_fma_f32 v70, v71, s28, -v177
	v_exp_f32_e32 v178, v70
	v_fma_f32 v70, v72, s28, -v177
	v_exp_f32_e32 v179, v70
	v_fma_f32 v70, v73, s28, -v177
	v_exp_f32_e32 v73, v70
	v_fma_f32 v70, v74, s28, -v177
	v_exp_f32_e32 v74, v70
	v_fma_f32 v70, v75, s28, -v177
	v_exp_f32_e32 v75, v70
	v_fma_f32 v70, v76, s28, -v177
	v_fma_f32 v66, v66, s28, -v177
	v_exp_f32_e32 v76, v70
	v_fma_f32 v70, v77, s28, -v177
	v_exp_f32_e32 v66, v66
	v_fma_f32 v67, v67, s28, -v177
	v_exp_f32_e32 v77, v70
	v_fma_f32 v70, v78, s28, -v177
	v_exp_f32_e32 v67, v67
	v_fma_f32 v68, v68, s28, -v177
	v_exp_f32_e32 v78, v70
	v_fma_f32 v70, v79, s28, -v177
	v_exp_f32_e32 v68, v68
	v_fma_f32 v69, v69, s28, -v177
	v_exp_f32_e32 v79, v70
	v_fma_f32 v70, v80, s28, -v177
	v_exp_f32_e32 v69, v69
	v_exp_f32_e32 v80, v70
	v_sub_f32_e32 v70, v176, v177
	v_exp_f32_e32 v176, v70
	v_add_f32_e32 v70, 0, v66
	v_add_f32_e32 v70, v67, v70
	v_add_f32_e32 v70, v68, v70
	v_add_f32_e32 v70, v69, v70
	v_add_f32_e32 v70, v81, v70
	v_add_f32_e32 v70, v178, v70
	v_add_f32_e32 v70, v179, v70
	v_add_f32_e32 v70, v73, v70
	v_add_f32_e32 v70, v74, v70
	v_add_f32_e32 v70, v75, v70
	v_add_f32_e32 v70, v76, v70
	v_add_f32_e32 v70, v77, v70
	v_add_f32_e32 v70, v78, v70
	v_mul_f32_e32 v0, 0x3e0293ee, v0
	v_add_f32_e32 v70, v79, v70
	v_exp_f32_e32 v0, v0
	v_add_f32_e32 v70, v80, v70
	v_cvt_pk_bf16_f32 v73, v179, v73
	v_add_u32_e32 v179, 0x8800, v165
	v_add_f32_e32 v148, v176, v70
	v_cvt_pk_bf16_f32 v70, v66, v67
	v_cvt_pk_bf16_f32 v71, v68, v69
	v_cvt_pk_bf16_f32 v72, v81, v178
	v_cvt_pk_bf16_f32 v66, v74, v75
	v_cvt_pk_bf16_f32 v67, v76, v77
	v_cvt_pk_bf16_f32 v68, v78, v79
	v_cvt_pk_bf16_f32 v69, v80, v176
	ds_read2_b64 v[74:77], v179 offset1:2
	ds_read2_b64 v[78:81], v179 offset0:4 offset1:6
	v_pk_mul_f32 v[64:65], v[64:65], v[0:1] op_sel_hi:[1,0]
	v_pk_mul_f32 v[62:63], v[62:63], v[0:1] op_sel_hi:[1,0]
	v_pk_mul_f32 v[60:61], v[60:61], v[0:1] op_sel_hi:[1,0]
	v_pk_mul_f32 v[58:59], v[58:59], v[0:1] op_sel_hi:[1,0]
	v_pk_mul_f32 v[56:57], v[56:57], v[0:1] op_sel_hi:[1,0]
	v_pk_mul_f32 v[54:55], v[54:55], v[0:1] op_sel_hi:[1,0]
	v_pk_mul_f32 v[52:53], v[52:53], v[0:1] op_sel_hi:[1,0]
	v_pk_mul_f32 v[50:51], v[50:51], v[0:1] op_sel_hi:[1,0]
	v_add_u32_e32 v176, 0x9000, v165
	v_pk_mul_f32 v[48:49], v[48:49], v[0:1] op_sel_hi:[1,0]
	s_waitcnt lgkmcnt(1)
	v_mfma_f32_32x32x16_bf16 v[50:65], v[74:77], v[70:73], v[50:65]
	ds_read2_b64 v[74:77], v176 offset0:32 offset1:34
	v_mul_f32_e64 v46, v46, v0
	v_mul_f32_e64 v47, v47, v0
	v_mul_f32_e64 v44, v44, v0
	v_mul_f32_e64 v45, v45, v0
	v_pk_mul_f32 v[42:43], v[42:43], v[0:1] op_sel_hi:[1,0]
	v_pk_mul_f32 v[40:41], v[40:41], v[0:1] op_sel_hi:[1,0]
	v_pk_mul_f32 v[38:39], v[38:39], v[0:1] op_sel_hi:[1,0]
	v_pk_mul_f32 v[36:37], v[36:37], v[0:1] op_sel_hi:[1,0]
	v_pk_mul_f32 v[34:35], v[34:35], v[0:1] op_sel_hi:[1,0]
	v_add_u32_e32 v177, 0x9800, v165
	v_pk_mul_f32 v[32:33], v[32:33], v[0:1] op_sel_hi:[1,0]
	s_waitcnt lgkmcnt(0)
	v_mfma_f32_32x32x16_bf16 v[34:49], v[74:77], v[70:73], v[34:49]
	ds_read2_b64 v[74:77], v176 offset0:36 offset1:38
	v_mul_f32_e64 v30, v30, v0
	v_mul_f32_e64 v31, v31, v0
	v_mul_f32_e64 v28, v28, v0
	v_mul_f32_e64 v29, v29, v0
	v_pk_mul_f32 v[26:27], v[26:27], v[0:1] op_sel_hi:[1,0]
	v_pk_mul_f32 v[24:25], v[24:25], v[0:1] op_sel_hi:[1,0]
	v_pk_mul_f32 v[22:23], v[22:23], v[0:1] op_sel_hi:[1,0]
	v_pk_mul_f32 v[20:21], v[20:21], v[0:1] op_sel_hi:[1,0]
	s_waitcnt lgkmcnt(0)
	v_mfma_f32_32x32x16_bf16 v[34:49], v[74:77], v[66:69], v[34:49]
	ds_read2_b64 v[74:77], v177 offset0:64 offset1:66
	v_mul_f32_e64 v18, v18, v0
	v_mul_f32_e64 v19, v19, v0
	v_add_u32_e32 v178, 0xa000, v165
	v_mul_f32_e64 v16, v16, v0
	v_mul_f32_e64 v17, v17, v0
	v_pk_mul_f32 v[14:15], v[14:15], v[0:1] op_sel_hi:[1,0]
	v_pk_mul_f32 v[12:13], v[12:13], v[0:1] op_sel_hi:[1,0]
	v_pk_mul_f32 v[10:11], v[10:11], v[0:1] op_sel_hi:[1,0]
	s_waitcnt lgkmcnt(0)
	v_mfma_f32_32x32x16_bf16 v[18:33], v[74:77], v[70:73], v[18:33]
	ds_read2_b64 v[74:77], v177 offset0:68 offset1:70
	v_mul_f32_e64 v8, v8, v0
	v_mul_f32_e64 v9, v9, v0
	v_mul_f32_e64 v6, v6, v0
	v_mul_f32_e64 v7, v7, v0
	v_pk_mul_f32 v[4:5], v[4:5], v[0:1] op_sel_hi:[1,0]
	v_pk_mul_f32 v[2:3], v[2:3], v[0:1] op_sel_hi:[1,0]
	v_fmac_f32_e32 v148, v175, v0
	s_waitcnt lgkmcnt(0)
	v_mfma_f32_32x32x16_bf16 v[18:33], v[74:77], v[66:69], v[18:33]
	ds_read2_b64 v[74:77], v178 offset0:96 offset1:98
	s_waitcnt lgkmcnt(0)
	v_mfma_f32_32x32x16_bf16 v[2:17], v[74:77], v[70:73], v[2:17]
	ds_read2_b64 v[70:73], v178 offset0:100 offset1:102
	s_waitcnt lgkmcnt(0)
	s_barrier
	v_mfma_f32_32x32x16_bf16 v[50:65], v[78:81], v[66:69], v[50:65]
	v_mfma_f32_32x32x16_bf16 v[2:17], v[70:73], v[66:69], v[2:17]
	s_cbranch_scc1 .LBB0_592
	s_waitcnt vmcnt(7)
	ds_write_b128 v160, v[118:121]
	s_waitcnt vmcnt(6)
	ds_write2_b64 v166, v[114:115], v[116:117] offset1:1
	s_waitcnt vmcnt(5)
	ds_write_b128 v160, v[126:129] offset:8704
	s_waitcnt vmcnt(4)
	ds_write2_b64 v167, v[122:123], v[124:125] offset1:1
	s_waitcnt vmcnt(3)
	ds_write_b128 v160, v[134:137] offset:17408
	s_waitcnt vmcnt(2)
	ds_write2_b64 v168, v[130:131], v[132:133] offset1:1
	s_waitcnt vmcnt(1)
	ds_write_b128 v160, v[142:145] offset:26112
	s_waitcnt vmcnt(0)
	ds_write2_b64 v169, v[138:139], v[140:141] offset1:1
	s_waitcnt lgkmcnt(0)
	s_barrier
	ds_read_b128 v[66:69], v159
	ds_read_b128 v[114:117], v159 offset:32
	s_waitcnt lgkmcnt(1)
	v_mfma_f32_32x32x16_bf16 v[66:81], v[66:69], v[110:113], 0
	v_readlane_b32 s1, v253, 17
	s_mov_b32 s4, 0xf149f2ca
	s_waitcnt lgkmcnt(0)
	v_mfma_f32_32x32x16_bf16 v[66:81], v[114:117], v[106:109], v[66:81]
	ds_read_b128 v[106:109], v159 offset:64
	ds_read_b128 v[110:113], v159 offset:96
	s_waitcnt lgkmcnt(1)
	v_mfma_f32_32x32x16_bf16 v[66:81], v[106:109], v[102:105], v[66:81]
	s_waitcnt lgkmcnt(0)
	v_mfma_f32_32x32x16_bf16 v[66:81], v[110:113], v[98:101], v[66:81]
	ds_read_b128 v[98:101], v159 offset:128
	ds_read_b128 v[102:105], v159 offset:160
	s_waitcnt lgkmcnt(1)
	v_mfma_f32_32x32x16_bf16 v[66:81], v[98:101], v[94:97], v[66:81]
	v_ashrrev_i32_e32 v100, 6, v157
	s_waitcnt lgkmcnt(0)
	v_mfma_f32_32x32x16_bf16 v[66:81], v[102:105], v[90:93], v[66:81]
	ds_read_b128 v[90:93], v159 offset:192
	ds_read_b128 v[94:97], v159 offset:224
	s_waitcnt lgkmcnt(1)
	v_mfma_f32_32x32x16_bf16 v[66:81], v[90:93], v[86:89], v[66:81]
	ds_read2_b64 v[86:89], v179 offset1:2
	s_waitcnt lgkmcnt(1)
	v_mfma_f32_32x32x16_bf16 v[66:81], v[94:97], v[82:85], v[66:81]
	ds_read2_b64 v[90:93], v179 offset0:4 offset1:6
	ds_read2_b64 v[94:97], v176 offset0:32 offset1:34
	s_nop 9
	v_max_f32_e32 v0, v67, v67
	v_max_f32_e32 v82, v66, v66
	v_max_f32_e32 v0, v82, v0
	v_max3_f32 v0, v0, v68, v69
	v_max3_f32 v0, v0, v70, v71
	v_max3_f32 v0, v0, v72, v73
	v_max3_f32 v0, v0, v74, v75
	v_max3_f32 v0, v0, v76, v77
	v_max3_f32 v0, v0, v78, v79
	v_max3_f32 v0, v0, v80, v81
	v_mov_b32_e32 v83, v0
	v_mov_b32_e32 v84, v81
	v_and_b32_e32 v82, 1, v100
	v_permlane32_swap_b32 v83, v0
	s_waitcnt lgkmcnt(0)
	v_max3_f32 v85, v149, v0, v83
	v_sub_f32_e32 v0, v149, v85
	v_pk_mul_f32 v[98:99], v[84:85], s[28:29] op_sel_hi:[1,0]
	v_mul_f32_e32 v0, 0x3e0293ee, v0
	v_fma_f32 v66, v66, s28, -v99
	v_fma_f32 v67, v67, s28, -v99
	v_fma_f32 v68, v68, s28, -v99
	v_fma_f32 v69, v69, s28, -v99
	v_fma_f32 v70, v70, s28, -v99
	v_fma_f32 v71, v71, s28, -v99
	v_fma_f32 v72, v72, s28, -v99
	v_fma_f32 v73, v73, s28, -v99
	v_fma_f32 v74, v74, s28, -v99
	v_fma_f32 v75, v75, s28, -v99
	v_fma_f32 v76, v76, s28, -v99
	v_fma_f32 v77, v77, s28, -v99
	v_fma_f32 v78, v78, s28, -v99
	v_fma_f32 v79, v79, s28, -v99
	v_fma_f32 v80, v80, s28, -v99
	v_sub_f32_e32 v81, v98, v99
	v_exp_f32_e32 v0, v0
	v_exp_f32_e32 v83, v66
	v_exp_f32_e32 v84, v67
	v_exp_f32_e32 v98, v68
	v_exp_f32_e32 v99, v69
	v_exp_f32_e32 v101, v70
	v_exp_f32_e32 v102, v71
	v_exp_f32_e32 v103, v72
	v_exp_f32_e32 v104, v73
	v_exp_f32_e32 v105, v74
	v_exp_f32_e32 v106, v75
	v_exp_f32_e32 v107, v76
	v_exp_f32_e32 v108, v77
	v_pk_mul_f32 v[48:49], v[48:49], v[0:1] op_sel_hi:[1,0]
	v_pk_mul_f32 v[46:47], v[46:47], v[0:1] op_sel_hi:[1,0]
	v_cvt_pk_bf16_f32 v66, v83, v84
	v_cvt_pk_bf16_f32 v67, v98, v99
	v_cvt_pk_bf16_f32 v68, v101, v102
	v_cvt_pk_bf16_f32 v69, v103, v104
	v_pk_mul_f32 v[44:45], v[44:45], v[0:1] op_sel_hi:[1,0]
	v_pk_mul_f32 v[42:43], v[42:43], v[0:1] op_sel_hi:[1,0]
	v_pk_mul_f32 v[40:41], v[40:41], v[0:1] op_sel_hi:[1,0]
	v_pk_mul_f32 v[38:39], v[38:39], v[0:1] op_sel_hi:[1,0]
	v_pk_mul_f32 v[36:37], v[36:37], v[0:1] op_sel_hi:[1,0]
	v_pk_mul_f32 v[34:35], v[34:35], v[0:1] op_sel_hi:[1,0]
	ds_read2_b64 v[74:77], v176 offset0:36 offset1:38
	v_exp_f32_e32 v109, v78
	v_exp_f32_e32 v110, v79
	v_exp_f32_e32 v111, v80
	v_exp_f32_e32 v112, v81
	v_mfma_f32_32x32x16_bf16 v[34:49], v[94:97], v[66:69], v[34:49]
	ds_read2_b64 v[78:81], v177 offset0:64 offset1:66
	v_cvt_pk_bf16_f32 v70, v105, v106
	v_cvt_pk_bf16_f32 v71, v107, v108
	v_cvt_pk_bf16_f32 v72, v109, v110
	v_cvt_pk_bf16_f32 v73, v111, v112
	v_pk_mul_f32 v[32:33], v[32:33], v[0:1] op_sel_hi:[1,0]
	v_pk_mul_f32 v[30:31], v[30:31], v[0:1] op_sel_hi:[1,0]
	v_pk_mul_f32 v[28:29], v[28:29], v[0:1] op_sel_hi:[1,0]
	v_pk_mul_f32 v[26:27], v[26:27], v[0:1] op_sel_hi:[1,0]
	v_pk_mul_f32 v[24:25], v[24:25], v[0:1] op_sel_hi:[1,0]
	v_pk_mul_f32 v[22:23], v[22:23], v[0:1] op_sel_hi:[1,0]
	v_pk_mul_f32 v[20:21], v[20:21], v[0:1] op_sel_hi:[1,0]
	v_pk_mul_f32 v[18:19], v[18:19], v[0:1] op_sel_hi:[1,0]
	s_waitcnt lgkmcnt(1)
	v_mfma_f32_32x32x16_bf16 v[34:49], v[74:77], v[70:73], v[34:49]
	ds_read2_b64 v[74:77], v177 offset0:68 offset1:70
	v_mul_f32_e64 v64, v64, v0
	v_mul_f32_e64 v65, v65, v0
	v_mul_f32_e64 v62, v62, v0
	v_mul_f32_e64 v63, v63, v0
	v_pk_mul_f32 v[60:61], v[60:61], v[0:1] op_sel_hi:[1,0]
	v_pk_mul_f32 v[58:59], v[58:59], v[0:1] op_sel_hi:[1,0]
	v_pk_mul_f32 v[56:57], v[56:57], v[0:1] op_sel_hi:[1,0]
	v_pk_mul_f32 v[54:55], v[54:55], v[0:1] op_sel_hi:[1,0]
	s_waitcnt lgkmcnt(1)
	v_mfma_f32_32x32x16_bf16 v[18:33], v[78:81], v[66:69], v[18:33]
	v_add_f32_e32 v78, 0, v83
	v_add_f32_e32 v78, v84, v78
	v_add_f32_e32 v78, v98, v78
	v_add_f32_e32 v78, v99, v78
	v_add_f32_e32 v83, v101, v78
	ds_read2_b64 v[78:81], v178 offset0:96 offset1:98
	v_pk_mul_f32 v[52:53], v[52:53], v[0:1] op_sel_hi:[1,0]
	s_waitcnt lgkmcnt(1)
	v_mfma_f32_32x32x16_bf16 v[18:33], v[74:77], v[70:73], v[18:33]
	v_add_f32_e32 v74, v102, v83
	v_add_f32_e32 v74, v103, v74
	v_add_f32_e32 v74, v104, v74
	v_add_f32_e32 v74, v105, v74
	v_mul_f32_e64 v50, v50, v0
	v_mul_f32_e64 v51, v51, v0
	v_add_f32_e32 v74, v106, v74
	v_pk_mul_f32 v[16:17], v[16:17], v[0:1] op_sel_hi:[1,0]
	v_mfma_f32_32x32x16_bf16 v[50:65], v[86:89], v[66:69], v[50:65]
	v_mul_f32_e64 v14, v14, v0
	v_mul_f32_e64 v15, v15, v0
	v_mul_f32_e64 v12, v12, v0
	v_mul_f32_e64 v13, v13, v0
	v_mul_f32_e64 v10, v10, v0
	v_mul_f32_e64 v11, v11, v0
	v_pk_mul_f32 v[8:9], v[8:9], v[0:1] op_sel_hi:[1,0]
	v_pk_mul_f32 v[6:7], v[6:7], v[0:1] op_sel_hi:[1,0]
	v_pk_mul_f32 v[4:5], v[4:5], v[0:1] op_sel_hi:[1,0]
	v_pk_mul_f32 v[2:3], v[2:3], v[0:1] op_sel_hi:[1,0]
	v_add_f32_e32 v83, v107, v74
	ds_read2_b64 v[74:77], v178 offset0:100 offset1:102
	s_waitcnt lgkmcnt(1)
	v_mfma_f32_32x32x16_bf16 v[2:17], v[78:81], v[66:69], v[2:17]
	v_add_f32_e32 v66, v108, v83
	v_add_f32_e32 v66, v109, v66
	v_add_f32_e32 v66, v110, v66
	v_add_f32_e32 v66, v111, v66
	v_add_f32_e32 v66, v112, v66
	v_fmac_f32_e32 v66, v148, v0
	v_mov_b32_e32 v0, v66
	v_mfma_f32_32x32x16_bf16 v[50:65], v[90:93], v[70:73], v[50:65]
	v_lshlrev_b32_e32 v67, 2, v155
	s_nop 1
	v_permlane32_swap_b32 v0, v66
	s_waitcnt lgkmcnt(0)
	s_barrier
	v_add_f32_e32 v0, v66, v0
	v_lshlrev_b32_e32 v66, 9, v100
	v_add3_u32 v66, s1, v66, v67
	ds_write2st64_b32 v66, v85, v0 offset1:1
	v_lshlrev_b32_e32 v0, 14, v100
	v_add3_u32 v0, 0, v0, v67
	v_mfma_f32_32x32x16_bf16 v[2:17], v[74:77], v[70:73], v[2:17]
	s_nop 1
	ds_write2st64_b32 v0, v50, v51 offset1:1
	ds_write2st64_b32 v0, v52, v53 offset0:2 offset1:3
	ds_write2st64_b32 v0, v54, v55 offset0:4 offset1:5
	ds_write2st64_b32 v0, v56, v57 offset0:6 offset1:7
	ds_write2st64_b32 v0, v58, v59 offset0:8 offset1:9
	ds_write2st64_b32 v0, v60, v61 offset0:10 offset1:11
	ds_write2st64_b32 v0, v62, v63 offset0:12 offset1:13
	ds_write2st64_b32 v0, v64, v65 offset0:14 offset1:15
	ds_write2st64_b32 v0, v34, v35 offset0:16 offset1:17
	ds_write2st64_b32 v0, v36, v37 offset0:18 offset1:19
	ds_write2st64_b32 v0, v38, v39 offset0:20 offset1:21
	ds_write2st64_b32 v0, v40, v41 offset0:22 offset1:23
	ds_write2st64_b32 v0, v42, v43 offset0:24 offset1:25
	ds_write2st64_b32 v0, v44, v45 offset0:26 offset1:27
	ds_write2st64_b32 v0, v46, v47 offset0:28 offset1:29
	ds_write2st64_b32 v0, v48, v49 offset0:30 offset1:31
	ds_write2st64_b32 v0, v18, v19 offset0:32 offset1:33
	ds_write2st64_b32 v0, v20, v21 offset0:34 offset1:35
	ds_write2st64_b32 v0, v22, v23 offset0:36 offset1:37
	ds_write2st64_b32 v0, v24, v25 offset0:38 offset1:39
	ds_write2st64_b32 v0, v26, v27 offset0:40 offset1:41
	ds_write2st64_b32 v0, v28, v29 offset0:42 offset1:43
	ds_write2st64_b32 v0, v30, v31 offset0:44 offset1:45
	ds_write2st64_b32 v0, v32, v33 offset0:46 offset1:47
	ds_write2st64_b32 v0, v2, v3 offset0:48 offset1:49
	ds_write2st64_b32 v0, v4, v5 offset0:50 offset1:51
	ds_write2st64_b32 v0, v6, v7 offset0:52 offset1:53
	ds_write2st64_b32 v0, v8, v9 offset0:54 offset1:55
	ds_write2st64_b32 v0, v10, v11 offset0:56 offset1:57
	ds_write2st64_b32 v0, v12, v13 offset0:58 offset1:59
	ds_write2st64_b32 v0, v14, v15 offset0:60 offset1:61
	ds_write2st64_b32 v0, v16, v17 offset0:62 offset1:63
	v_lshlrev_b32_e32 v0, 9, v82
	v_add3_u32 v0, s1, v0, v67
	s_waitcnt lgkmcnt(0)
	s_barrier
	ds_read2st64_b32 v[4:5], v0 offset1:1
	ds_read2st64_b32 v[6:7], v0 offset0:4 offset1:5
	ds_read2st64_b32 v[8:9], v0 offset0:8 offset1:9
	ds_read2st64_b32 v[10:11], v0 offset0:12 offset1:13
	s_mov_b32 s1, s31
	s_lshl_b64 s[0:1], s[0:1], 11
	s_waitcnt lgkmcnt(2)
	v_max3_f32 v0, v4, s4, v6
	s_add_u32 s4, s80, s0
	s_waitcnt lgkmcnt(0)
	v_max3_f32 v0, v0, v8, v10
	v_sub_f32_e32 v2, v4, v0
	v_mul_f32_e32 v2, 0x3e0293ee, v2
	v_exp_f32_e32 v3, v2
	v_sub_f32_e32 v2, v6, v0
	v_mul_f32_e32 v2, 0x3e0293ee, v2
	v_exp_f32_e32 v2, v2
	v_mov_b32_e32 v4, v7
	s_addc_u32 s5, s81, s1
	v_pk_mul_f32 v[6:7], v[4:5], v[2:3]
	v_sub_f32_e32 v4, v8, v0
	v_sub_f32_e32 v0, v10, v0
	v_mul_f32_e32 v4, 0x3e0293ee, v4
	v_mul_f32_e32 v0, 0x3e0293ee, v0
	v_exp_f32_e32 v5, v4
	v_exp_f32_e32 v4, v0
	v_add_f32_e32 v0, 0, v7
	v_mov_b32_e32 v8, v11
	v_add_f32_e32 v0, v6, v0
	v_pk_mul_f32 v[6:7], v[8:9], v[4:5]
	s_nop 0
	v_add_f32_e32 v0, v7, v0
	v_add_f32_e32 v0, v6, v0
	v_div_scale_f32 v6, s[0:1], v0, v0, 1.0
	v_rcp_f32_e32 v7, v6
	s_lshl_b32 s0, s6, 1
	s_add_u32 s0, s4, s0
	s_addc_u32 s1, s5, 0
	v_fma_f32 v8, -v6, v7, 1.0
	v_fmac_f32_e32 v7, v8, v7
	v_div_scale_f32 v8, vcc, 1.0, v0, 1.0
	v_mul_f32_e32 v9, v8, v7
	v_fma_f32 v10, -v6, v9, v8
	v_fmac_f32_e32 v9, v10, v7
	v_fma_f32 v6, -v6, v9, v8
	v_div_fmas_f32 v6, v6, v7, v9
	v_div_fixup_f32 v0, v6, v0, 1.0
	v_lshl_add_u32 v6, v82, 14, 0
	v_lshlrev_b32_e32 v7, 12, v154
	v_add3_u32 v7, v6, v7, v67
	ds_read2st64_b32 v[8:9], v7 offset1:1
	ds_read2st64_b32 v[10:11], v7 offset0:128 offset1:129
	v_mov_b32_e32 v6, v3
	v_add_u32_e32 v24, 0x10000, v7
	v_add_u32_e32 v25, 0x18000, v7
	v_add_u32_e32 v27, 0x10100, v7
	v_add_u32_e32 v28, 0x18100, v7
	ds_read2st64_b32 v[12:13], v7 offset0:2 offset1:3
	ds_read2st64_b32 v[14:15], v7 offset0:4 offset1:5
	ds_read2st64_b32 v[16:17], v7 offset0:6 offset1:7
	s_waitcnt lgkmcnt(4)
	v_pk_fma_f32 v[8:9], v[8:9], v[6:7], 0 op_sel_hi:[1,0,0]
	v_add_u32_e32 v31, 0x18300, v7
	ds_read2st64_b32 v[18:19], v7 offset0:130 offset1:131
	ds_read2st64_b32 v[20:21], v7 offset0:132 offset1:133
	ds_read2st64_b32 v[22:23], v7 offset0:134 offset1:135
	s_waitcnt lgkmcnt(6)
	v_pk_fma_f32 v[8:9], v[10:11], v[2:3], v[8:9] op_sel_hi:[1,0,1]
	v_mov_b32_e32 v10, v5
	v_add_u32_e32 v3, 0x10200, v7
	v_add_u32_e32 v5, 0x18200, v7
	v_add_u32_e32 v11, 0x10300, v7
	ds_read_b32 v24, v24
	ds_read_b32 v26, v25
	ds_read_b32 v25, v27
	ds_read_b32 v27, v28
	ds_read_b32 v28, v3
	ds_read_b32 v30, v5
	ds_read_b32 v29, v11
	ds_read_b32 v31, v31
	s_waitcnt lgkmcnt(13)
	v_pk_fma_f32 v[12:13], v[6:7], v[12:13], 0 op_sel_hi:[0,1,0]
	s_waitcnt lgkmcnt(5)
	v_pk_fma_f32 v[8:9], v[10:11], v[24:25], v[8:9] op_sel_hi:[0,1,1]
	v_pk_fma_f32 v[12:13], v[2:3], v[18:19], v[12:13] op_sel_hi:[0,1,1]
	v_add_u32_e32 v3, 0x10400, v7
	v_pk_fma_f32 v[14:15], v[6:7], v[14:15], 0 op_sel_hi:[0,1,0]
	s_waitcnt lgkmcnt(4)
	v_pk_fma_f32 v[8:9], v[4:5], v[26:27], v[8:9] op_sel_hi:[0,1,1]
	s_waitcnt lgkmcnt(1)
	v_pk_fma_f32 v[12:13], v[10:11], v[28:29], v[12:13] op_sel_hi:[0,1,1]
	v_add_u32_e32 v11, 0x10500, v7
	v_add_u32_e32 v24, 0x18500, v7
	v_pk_fma_f32 v[14:15], v[2:3], v[20:21], v[14:15] op_sel_hi:[0,1,1]
	v_add_u32_e32 v25, 0x10600, v7
	v_add_u32_e32 v26, 0x18600, v7
	v_add_u32_e32 v27, 0x10700, v7
	s_waitcnt lgkmcnt(0)
	v_pk_fma_f32 v[12:13], v[4:5], v[30:31], v[12:13] op_sel_hi:[0,1,1]
	v_add_u32_e32 v5, 0x18400, v7
	v_add_u32_e32 v28, 0x18700, v7
	ds_read_b32 v18, v3
	ds_read_b32 v20, v5
	ds_read_b32 v19, v11
	ds_read_b32 v21, v24
	ds_read_b32 v24, v25
	ds_read_b32 v26, v26
	ds_read_b32 v25, v27
	ds_read_b32 v27, v28
	s_waitcnt lgkmcnt(5)
	v_pk_fma_f32 v[14:15], v[10:11], v[18:19], v[14:15] op_sel_hi:[0,1,1]
	s_waitcnt lgkmcnt(4)
	v_pk_fma_f32 v[14:15], v[4:5], v[20:21], v[14:15] op_sel_hi:[0,1,1]
	ds_read2st64_b32 v[18:19], v7 offset0:8 offset1:9
	ds_read2st64_b32 v[20:21], v7 offset0:136 offset1:137
	v_pk_fma_f32 v[16:17], v[6:7], v[16:17], 0 op_sel_hi:[0,1,0]
	v_pk_fma_f32 v[16:17], v[2:3], v[22:23], v[16:17] op_sel_hi:[0,1,1]
	s_waitcnt lgkmcnt(3)
	v_pk_fma_f32 v[16:17], v[10:11], v[24:25], v[16:17] op_sel_hi:[0,1,1]
	s_waitcnt lgkmcnt(2)
	v_pk_fma_f32 v[16:17], v[4:5], v[26:27], v[16:17] op_sel_hi:[0,1,1]
	v_add_u32_e32 v3, 0x10800, v7
	v_add_u32_e32 v35, 0x18900, v7
	ds_read2st64_b32 v[22:23], v7 offset0:10 offset1:11
	ds_read2st64_b32 v[24:25], v7 offset0:12 offset1:13
	ds_read2st64_b32 v[26:27], v7 offset0:14 offset1:15
	s_waitcnt lgkmcnt(4)
	v_pk_fma_f32 v[18:19], v[6:7], v[18:19], 0 op_sel_hi:[0,1,0]
	v_add_u32_e32 v36, 0x10a00, v7
	v_add_u32_e32 v37, 0x18a00, v7
	v_add_u32_e32 v39, 0x10b00, v7
	v_add_u32_e32 v5, 0x18800, v7
	v_add_u32_e32 v11, 0x10900, v7
	ds_read2st64_b32 v[28:29], v7 offset0:138 offset1:139
	ds_read2st64_b32 v[30:31], v7 offset0:140 offset1:141
	ds_read2st64_b32 v[32:33], v7 offset0:142 offset1:143
	s_waitcnt lgkmcnt(6)
	v_pk_fma_f32 v[18:19], v[2:3], v[20:21], v[18:19] op_sel_hi:[0,1,1]
	v_add_u32_e32 v40, 0x18b00, v7
	ds_read_b32 v20, v3
	ds_read_b32 v34, v5
	ds_read_b32 v21, v11
	ds_read_b32 v35, v35
	ds_read_b32 v36, v36
	ds_read_b32 v38, v37
	ds_read_b32 v37, v39
	ds_read_b32 v39, v40
	s_waitcnt lgkmcnt(5)
	v_pk_fma_f32 v[18:19], v[10:11], v[20:21], v[18:19] op_sel_hi:[0,1,1]
	v_pk_fma_f32 v[20:21], v[6:7], v[22:23], 0 op_sel_hi:[0,1,0]
	v_pk_fma_f32 v[20:21], v[2:3], v[28:29], v[20:21] op_sel_hi:[0,1,1]
	v_add_u32_e32 v3, 0x10c00, v7
	v_pk_fma_f32 v[22:23], v[6:7], v[24:25], 0 op_sel_hi:[0,1,0]
	s_waitcnt lgkmcnt(4)
	v_pk_fma_f32 v[18:19], v[4:5], v[34:35], v[18:19] op_sel_hi:[0,1,1]
	s_waitcnt lgkmcnt(1)
	v_pk_fma_f32 v[20:21], v[10:11], v[36:37], v[20:21] op_sel_hi:[0,1,1]
	v_add_u32_e32 v29, 0x18d00, v7
	v_pk_fma_f32 v[22:23], v[2:3], v[30:31], v[22:23] op_sel_hi:[0,1,1]
	v_add_u32_e32 v30, 0x10e00, v7
	v_add_u32_e32 v31, 0x18e00, v7
	v_add_u32_e32 v35, 0x10f00, v7
	s_waitcnt lgkmcnt(0)
	v_pk_fma_f32 v[20:21], v[4:5], v[38:39], v[20:21] op_sel_hi:[0,1,1]
	v_add_u32_e32 v5, 0x18c00, v7
	v_add_u32_e32 v11, 0x10d00, v7
	v_add_u32_e32 v7, 0x18f00, v7
	ds_read_b32 v24, v3
	ds_read_b32 v28, v5
	ds_read_b32 v25, v11
	ds_read_b32 v29, v29
	ds_read_b32 v30, v30
	ds_read_b32 v34, v31
	ds_read_b32 v31, v35
	ds_read_b32 v35, v7
	v_pk_fma_f32 v[6:7], v[6:7], v[26:27], 0 op_sel_hi:[0,1,0]
	v_pk_fma_f32 v[2:3], v[2:3], v[32:33], v[6:7] op_sel_hi:[0,1,1]
	s_waitcnt lgkmcnt(5)
	v_pk_fma_f32 v[22:23], v[10:11], v[24:25], v[22:23] op_sel_hi:[0,1,1]
	s_waitcnt lgkmcnt(1)
	v_pk_fma_f32 v[2:3], v[10:11], v[30:31], v[2:3] op_sel_hi:[0,1,1]
	v_pk_fma_f32 v[22:23], v[4:5], v[28:29], v[22:23] op_sel_hi:[0,1,1]
	s_waitcnt lgkmcnt(0)
	v_pk_fma_f32 v[2:3], v[4:5], v[34:35], v[2:3] op_sel_hi:[0,1,1]
	v_pk_mul_f32 v[8:9], v[8:9], v[0:1] op_sel_hi:[1,0]
	v_pk_mul_f32 v[12:13], v[0:1], v[12:13] op_sel_hi:[0,1]
	v_pk_mul_f32 v[14:15], v[0:1], v[14:15] op_sel_hi:[0,1]
	v_pk_mul_f32 v[16:17], v[0:1], v[16:17] op_sel_hi:[0,1]
	v_pk_mul_f32 v[18:19], v[0:1], v[18:19] op_sel_hi:[0,1]
	v_pk_mul_f32 v[20:21], v[0:1], v[20:21] op_sel_hi:[0,1]
	v_pk_mul_f32 v[22:23], v[0:1], v[22:23] op_sel_hi:[0,1]
	v_pk_mul_f32 v[2:3], v[0:1], v[2:3] op_sel_hi:[0,1]
	v_lshlrev_b32_e32 v0, 11, v147
	v_lshl_or_b32 v0, v82, 16, v0
	v_lshlrev_b32_e32 v6, 5, v154
	v_lshl_add_u64 v[4:5], s[0:1], 0, v[0:1]
	v_ashrrev_i32_e32 v7, 31, v6
	v_lshl_add_u64 v[4:5], v[6:7], 1, v[4:5]
	v_mov_b32_e32 v147, v1
	v_lshl_add_u64 v[4:5], v[4:5], 0, v[146:147]
	s_mov_b64 s[0:1], 0x4328400
	v_lshl_add_u64 v[6:7], v[4:5], 0, s[0:1]
	s_mov_b32 s0, 0x4328000
	v_add_co_u32_e32 v4, vcc, s0, v4
	v_cvt_pk_bf16_f32 v8, v8, v9
	v_cvt_pk_bf16_f32 v9, v12, v13
	v_addc_co_u32_e32 v5, vcc, 0, v5, vcc
	global_store_dwordx2 v[4:5], v[8:9], off offset:1024
	v_cvt_pk_bf16_f32 v4, v14, v15
	v_cvt_pk_bf16_f32 v5, v16, v17
	global_store_dwordx2 v[6:7], v[4:5], off offset:16
	v_cvt_pk_bf16_f32 v4, v18, v19
	v_cvt_pk_bf16_f32 v5, v20, v21
	global_store_dwordx2 v[6:7], v[4:5], off offset:32
	v_cvt_pk_bf16_f32 v4, v22, v23
	v_cvt_pk_bf16_f32 v5, v2, v3
	global_store_dwordx2 v[6:7], v[4:5], off offset:48
	s_barrier
	s_mov_b64 s[0:1], 0
